# v063 plus the no-longer-needed s_waitcnt lgkmcnt(0) after the 8 row-max permlane swaps removed and three dead bpermute-address computations deleted
# speedup vs baseline: 1.0026x; 1.0026x over previous
; template <int MODE>
; DI void bias_init(f32x16& s0, f32x16& s1, const TP& tp, float fbm, int hi) {
; #pragma unroll
;     for (int r = 0; r < 16; ++r) {
;         const int kvc = 16 * (r >> 3) + (r & 7);
;         if (MODE == 0) { s0[r] = __builtin_fmaf(-L2E, tp.cs[kvc + 8 * hi], fbm); s1[r] = __builtin_fmaf(-L2E, tp.cs[kvc + 32 + 8 * hi], fbm); }
;         else { s0[r] = __builtin_fmaf(tp.sl, (float)kvc, fbm); s1[r] = __builtin_fmaf(tp.sl, (float)(kvc + 32), fbm); }
;     }
; }
; DI float max3_asm(float a, float b, float c) { float r; asm("v_max3_f32 %0, %1, %2, %3" : "=v"(r) : "v"(a), "v"(b), "v"(c)); return r; }
; template <bool MASK>
; DI float mask_rowmax(f32x16& s0, f32x16& s1, const TP& tp) {
;     if (MASK) {
; #pragma unroll
;         for (int r = 0; r < 16; ++r) {
;             const int kvc = 16 * (r >> 3) + (r & 7);
;             const bool v0 = tp.sel && (kvc <= tp.lim) && (kvc > tp.lim2), v1 = tp.sel && (kvc + 32 <= tp.lim) && (kvc + 32 > tp.lim2);
;             s0[r] = v0 ? s0[r] : -1e30f; s1[r] = v1 ? s1[r] : -1e30f;
;         }
;     }
;     const float seed = __builtin_fminf(s0[15], s1[15]);
;     float ma = seed, mb = seed;
; #pragma unroll
;     for (int r = 0; r < 16; r += 2) { ma = max3_asm(ma, s0[r], s1[r]); mb = max3_asm(mb, s0[r + 1], s1[r + 1]); }
;     const float mx = fmaxf(ma, mb);
;     return fmaxf(mx, __shfl_xor(mx, 32));
; }
; template <int MODE, bool MASK, bool WITH_O>
; DI void attn_tile_t(lptr Kt, lptr Vt, const bf16x8 (&qf)[4], f32x16& o0, f32x16& o1, RowState& rs, const TP& tp, int lane) {
;     const int hi = lane >> 5;
;     f32x16 s0, s1;
;     bias_init<MODE>(s0, s1, tp, tp.fb - rs.mref, hi);
;     qk_acc(Kt, qf, s0, s1, lane);
;     const float mx = mask_rowmax<MASK>(s0, s1, tp);
;     const bool was = rs.seen; rs.seen = was || (mx > -1e29f);
;     const bool trig = (mx > 8.f) || (!was && mx > -1e29f && mx < -8.f);
;     if (__builtin_expect(__any(trig), 0)) {
.LBB0_493:
	s_lshl_b32 s2, s55, 8
	s_add_i32 s26, s2, 0
	s_mul_i32 s2, s55, 0x2300
	s_add_i32 s56, s26, s2
	s_mov_b64 s[2:3], -1
	s_cmp_le_i32 s31, s42
	v_sub_f32_e32 v156, v157, v160
	v_add3_u32 v161, s56, v131, v133
	v_lshl_add_u32 v162, v126, 2, s26
	s_cbranch_scc0 .LBB0_498
	ds_read_b128 v[34:37], v162 offset:36992
	ds_read_b128 v[38:41], v162 offset:36864
	ds_read_b128 v[42:45], v162 offset:36880
	ds_read_b128 v[46:49], v162 offset:37008
	ds_read_b128 v[50:53], v162 offset:36928
	ds_read_b128 v[54:57], v162 offset:37056
	ds_read_b128 v[58:61], v162 offset:36944
	ds_read_b128 v[62:65], v162 offset:37072
	ds_read_b128 v[166:169], v161 offset:4608
	ds_read_b128 v[216:219], v161
	ds_read_b128 v[228:231], v161 offset:32
	ds_read_b128 v[232:235], v161 offset:4640
	ds_read_b128 v[236:239], v161 offset:64
	ds_read_b128 v[240:243], v161 offset:4672
	ds_read_b128 v[244:247], v161 offset:96
	ds_read_b128 v[252:255], v161 offset:4704
	s_waitcnt lgkmcnt(13)
	v_pk_fma_f32 v[88:89], v[44:45], s[80:81], v[156:157] op_sel_hi:[1,0,0]
	s_waitcnt lgkmcnt(11)
	v_pk_fma_f32 v[92:93], v[52:53], s[80:81], v[156:157] op_sel_hi:[1,0,0]
	v_pk_fma_f32 v[84:85], v[40:41], s[80:81], v[156:157] op_sel_hi:[1,0,0]
	s_waitcnt lgkmcnt(9)
	v_pk_fma_f32 v[96:97], v[60:61], s[80:81], v[156:157] op_sel_hi:[1,0,0]
	v_pk_fma_f32 v[94:95], v[58:59], s[80:81], v[156:157] op_sel_hi:[1,0,0]
	v_pk_fma_f32 v[90:91], v[50:51], s[80:81], v[156:157] op_sel_hi:[1,0,0]
	v_pk_fma_f32 v[86:87], v[42:43], s[80:81], v[156:157] op_sel_hi:[1,0,0]
	v_pk_fma_f32 v[82:83], v[38:39], s[80:81], v[156:157] op_sel_hi:[1,0,0]
	s_waitcnt lgkmcnt(8)
	v_pk_fma_f32 v[80:81], v[64:65], s[80:81], v[156:157] op_sel_hi:[1,0,0]
	v_pk_fma_f32 v[76:77], v[56:57], s[80:81], v[156:157] op_sel_hi:[1,0,0]
	v_pk_fma_f32 v[72:73], v[48:49], s[80:81], v[156:157] op_sel_hi:[1,0,0]
	v_pk_fma_f32 v[68:69], v[36:37], s[80:81], v[156:157] op_sel_hi:[1,0,0]
	v_pk_fma_f32 v[78:79], v[62:63], s[80:81], v[156:157] op_sel_hi:[1,0,0]
	v_pk_fma_f32 v[74:75], v[54:55], s[80:81], v[156:157] op_sel_hi:[1,0,0]
	v_pk_fma_f32 v[70:71], v[46:47], s[80:81], v[156:157] op_sel_hi:[1,0,0]
	v_pk_fma_f32 v[66:67], v[34:35], s[80:81], v[156:157] op_sel_hi:[1,0,0]
	s_setprio 1
	s_waitcnt lgkmcnt(6)
	v_mfma_f32_32x32x16_bf16 v[82:97], v[216:219], v[98:101], v[82:97]
	v_mfma_f32_32x32x16_bf16 v[66:81], v[166:169], v[98:101], v[66:81]
	s_waitcnt lgkmcnt(5)
	v_mfma_f32_32x32x16_bf16 v[82:97], v[228:231], v[102:105], v[82:97]
	s_waitcnt lgkmcnt(4)
	v_mfma_f32_32x32x16_bf16 v[66:81], v[232:235], v[102:105], v[66:81]
	s_waitcnt lgkmcnt(3)
	v_mfma_f32_32x32x16_bf16 v[82:97], v[236:239], v[106:109], v[82:97]
	s_waitcnt lgkmcnt(2)
	v_mfma_f32_32x32x16_bf16 v[66:81], v[240:243], v[106:109], v[66:81]
	s_waitcnt lgkmcnt(1)
	v_mfma_f32_32x32x16_bf16 v[82:97], v[244:247], v[110:113], v[82:97]
	s_waitcnt lgkmcnt(0)
	v_mfma_f32_32x32x16_bf16 v[66:81], v[252:255], v[110:113], v[66:81]
	s_setprio 0
	v_add3_u32 v228, s56, v135, v141
	ds_read_b128 v[216:219], v228 offset:18432
	ds_read_b128 v[38:41], v228 offset:23040
	ds_read_b128 v[42:45], v228 offset:18464
	ds_read_b128 v[46:49], v228 offset:23072
	ds_read_b128 v[50:53], v228 offset:18496
	ds_read_b128 v[54:57], v228 offset:23104
	ds_read_b128 v[58:61], v228 offset:18528
	ds_read_b128 v[62:65], v228 offset:23136
	s_nop 1
	v_max_f32_e32 v34, v81, v81
	v_max_f32_e32 v35, v97, v97
	v_min_f32_e32 v34, v35, v34
	v_max3_f32 v35, v34, v82, v66
	v_max3_f32 v34, v34, v83, v67
	v_and_b32_e32 v36, 64, v209
	v_max3_f32 v35, v35, v84, v68
	v_max3_f32 v34, v34, v85, v69
	v_add_u32_e32 v36, 64, v36
	v_max3_f32 v35, v35, v86, v70
	v_max3_f32 v34, v34, v87, v71
	s_mov_b32 s2, 0xefa18f08
	v_max3_f32 v35, v35, v88, v72
	v_max3_f32 v34, v34, v89, v73
	s_mov_b64 s[28:29], -1
	v_max3_f32 v35, v35, v90, v74
	v_max3_f32 v34, v34, v91, v75
	v_max3_f32 v35, v35, v92, v76
	v_max3_f32 v34, v34, v93, v77
	v_max3_f32 v35, v35, v94, v78
	v_max3_f32 v34, v34, v95, v79
	v_max3_f32 v35, v35, v96, v80
	v_max3_f32 v34, v34, v97, v81
	v_max_f32_e32 v34, v34, v34
	v_max_f32_e32 v35, v35, v35
	v_max_f32_e32 v34, v35, v34
	v_mov_b32_e32 v35, v34
	s_nop 1
	v_permlane32_swap_b32_e32 v35, v34
	v_max_f32_e32 v165, v34, v35
	v_cmp_lt_f32_e64 s[26:27], s2, v165
	s_mov_b32 s2, 0x41000000
	v_cmp_lt_f32_e32 vcc, s2, v165
	s_mov_b32 s28, 0xc1000000
	v_cmp_gt_f32_e64 s[28:29], s28, v165
	s_and_b64 s[28:29], s[28:29], s[26:27]
	s_andn2_b64 s[28:29], s[28:29], s[22:23]
	s_or_b64 s[28:29], s[28:29], vcc
	s_and_b64 vcc, exec, s[28:29]
	v_mov_b32_e32 v163, v160
	v_mov_b32_e32 v164, v159
	s_cbranch_vccnz .LBB0_514

; DI float max3_asm(float a, float b, float c) { float r; asm("v_max3_f32 %0, %1, %2, %3" : "=v"(r) : "v"(a), "v"(b), "v"(c)); return r; }
; template <bool MASK>
; DI float mask_rowmax(f32x16& s0, f32x16& s1, const TP& tp) {
;     if (MASK) {
; #pragma unroll
;         for (int r = 0; r < 16; ++r) {
;             const int kvc = 16 * (r >> 3) + (r & 7);
;             const bool v0 = tp.sel && (kvc <= tp.lim) && (kvc > tp.lim2), v1 = tp.sel && (kvc + 32 <= tp.lim) && (kvc + 32 > tp.lim2);
;             s0[r] = v0 ? s0[r] : -1e30f; s1[r] = v1 ? s1[r] : -1e30f;
;         }
;     }
;     const float seed = __builtin_fminf(s0[15], s1[15]);
;     float ma = seed, mb = seed;
; #pragma unroll
;     for (int r = 0; r < 16; r += 2) { ma = max3_asm(ma, s0[r], s1[r]); mb = max3_asm(mb, s0[r + 1], s1[r + 1]); }
;     const float mx = fmaxf(ma, mb);
;     return fmaxf(mx, __shfl_xor(mx, 32));
; }
; template <int MODE, bool MASK, bool WITH_O>
; DI void attn_tile_t(lptr Kt, lptr Vt, const bf16x8 (&qf)[4], f32x16& o0, f32x16& o1, RowState& rs, const TP& tp, int lane) {
;     const int hi = lane >> 5;
;     f32x16 s0, s1;
;     bias_init<MODE>(s0, s1, tp, tp.fb - rs.mref, hi);
;     qk_acc(Kt, qf, s0, s1, lane);
;     const float mx = mask_rowmax<MASK>(s0, s1, tp);
;     const bool was = rs.seen; rs.seen = was || (mx > -1e29f);
;     const bool trig = (mx > 8.f) || (!was && mx > -1e29f && mx < -8.f);
;     if (__builtin_expect(__any(trig), 0)) {
.LBB0_498:
	s_and_b64 vcc, exec, s[2:3]
	s_cbranch_vccz .LBB0_503
	s_nop 8
	ds_read_b128 v[50:53], v162 offset:36992
	ds_read_b128 v[34:37], v162 offset:36864
	ds_read_b128 v[38:41], v162 offset:36880
	ds_read_b128 v[54:57], v162 offset:37008
	ds_read_b128 v[42:45], v162 offset:36928
	ds_read_b128 v[58:61], v162 offset:37056
	ds_read_b128 v[46:49], v162 offset:36944
	ds_read_b128 v[62:65], v162 offset:37072
	ds_read_b128 v[66:69], v161 offset:4608
	ds_read_b128 v[70:73], v161
	ds_read_b128 v[74:77], v161 offset:32
	ds_read_b128 v[78:81], v161 offset:4640
	ds_read_b128 v[82:85], v161 offset:64
	ds_read_b128 v[86:89], v161 offset:4672
	ds_read_b128 v[90:93], v161 offset:96
	ds_read_b128 v[94:97], v161 offset:4704
	s_waitcnt lgkmcnt(11)
	v_pk_fma_f32 v[44:45], v[44:45], s[80:81], v[156:157] op_sel_hi:[1,0,0]
	v_pk_fma_f32 v[40:41], v[40:41], s[80:81], v[156:157] op_sel_hi:[1,0,0]
	v_pk_fma_f32 v[36:37], v[36:37], s[80:81], v[156:157] op_sel_hi:[1,0,0]
	s_waitcnt lgkmcnt(9)
	v_pk_fma_f32 v[46:47], v[46:47], s[80:81], v[156:157] op_sel_hi:[1,0,0]
	v_pk_fma_f32 v[42:43], v[42:43], s[80:81], v[156:157] op_sel_hi:[1,0,0]
	v_pk_fma_f32 v[38:39], v[38:39], s[80:81], v[156:157] op_sel_hi:[1,0,0]
	v_pk_fma_f32 v[34:35], v[34:35], s[80:81], v[156:157] op_sel_hi:[1,0,0]
	v_pk_fma_f32 v[56:57], v[56:57], s[80:81], v[156:157] op_sel_hi:[1,0,0]
	v_pk_fma_f32 v[52:53], v[52:53], s[80:81], v[156:157] op_sel_hi:[1,0,0]
	v_pk_fma_f32 v[54:55], v[54:55], s[80:81], v[156:157] op_sel_hi:[1,0,0]
	v_pk_fma_f32 v[50:51], v[50:51], s[80:81], v[156:157] op_sel_hi:[1,0,0]
	v_pk_fma_f32 v[48:49], v[48:49], s[80:81], v[156:157] op_sel_hi:[1,0,0]
	s_waitcnt lgkmcnt(8)
	v_pk_fma_f32 v[64:65], v[64:65], s[80:81], v[156:157] op_sel_hi:[1,0,0]
	v_pk_fma_f32 v[60:61], v[60:61], s[80:81], v[156:157] op_sel_hi:[1,0,0]
	v_pk_fma_f32 v[62:63], v[62:63], s[80:81], v[156:157] op_sel_hi:[1,0,0]
	v_pk_fma_f32 v[58:59], v[58:59], s[80:81], v[156:157] op_sel_hi:[1,0,0]
	s_setprio 1
	s_waitcnt lgkmcnt(6)
	v_mfma_f32_32x32x16_bf16 v[34:49], v[70:73], v[98:101], v[34:49]
	v_mfma_f32_32x32x16_bf16 v[50:65], v[66:69], v[98:101], v[50:65]
	s_waitcnt lgkmcnt(5)
	v_mfma_f32_32x32x16_bf16 v[34:49], v[74:77], v[102:105], v[34:49]
	s_waitcnt lgkmcnt(4)
	v_mfma_f32_32x32x16_bf16 v[50:65], v[78:81], v[102:105], v[50:65]
	s_waitcnt lgkmcnt(3)
	v_mfma_f32_32x32x16_bf16 v[34:49], v[82:85], v[106:109], v[34:49]
	s_waitcnt lgkmcnt(2)
	v_mfma_f32_32x32x16_bf16 v[50:65], v[86:89], v[106:109], v[50:65]
	s_waitcnt lgkmcnt(1)
	v_mfma_f32_32x32x16_bf16 v[34:49], v[90:93], v[110:113], v[34:49]
	s_waitcnt lgkmcnt(0)
	v_mfma_f32_32x32x16_bf16 v[50:65], v[94:97], v[110:113], v[50:65]
	s_setprio 0
	v_cmp_lt_i32_e32 vcc, 0, v158
	s_mov_b32 s2, 0xefa18f08
	s_nop 6
	v_cndmask_b32_e32 v72, v210, v35, vcc
	v_cmp_lt_i32_e64 s[98:99], -1, v158
	v_cmp_lt_i32_e64 s[100:101], 32, v158
	v_cmp_lt_i32_e32 vcc, 31, v158
	v_cndmask_b32_e64 v76, v210, v34, s[98:99]
	v_cndmask_b32_e64 v66, v210, v51, s[100:101]
	v_cndmask_b32_e32 v68, v210, v50, vcc
	v_cmp_lt_i32_e64 s[98:99], 2, v158
	v_cmp_lt_i32_e64 s[100:101], 1, v158
	v_cmp_lt_i32_e32 vcc, 34, v158
	v_cndmask_b32_e64 v71, v210, v37, s[98:99]
	v_cndmask_b32_e64 v75, v210, v36, s[100:101]
	v_cndmask_b32_e32 v53, v210, v53, vcc
	v_cmp_lt_i32_e64 s[98:99], 33, v158
	v_cmp_lt_i32_e64 s[100:101], 4, v158
	v_cmp_lt_i32_e32 vcc, 3, v158
	v_cndmask_b32_e64 v67, v210, v52, s[98:99]
	v_cndmask_b32_e64 v70, v210, v39, s[100:101]
	v_cndmask_b32_e32 v74, v210, v38, vcc
	v_cmp_lt_i32_e64 s[98:99], 36, v158
	v_cmp_lt_i32_e64 s[100:101], 35, v158
	v_cmp_lt_i32_e32 vcc, 6, v158
	v_cndmask_b32_e64 v51, v210, v55, s[98:99]
	v_cndmask_b32_e64 v54, v210, v54, s[100:101]
	v_cndmask_b32_e32 v69, v210, v41, vcc
	v_cmp_lt_i32_e64 s[98:99], 5, v158
	v_cmp_lt_i32_e64 s[100:101], 38, v158
	v_cmp_lt_i32_e32 vcc, 37, v158
	v_cndmask_b32_e64 v73, v210, v40, s[98:99]
	v_cndmask_b32_e64 v50, v210, v57, s[100:101]
	v_cndmask_b32_e32 v52, v210, v56, vcc
	v_cmp_lt_i32_e64 s[98:99], 16, v158
	v_cmp_lt_i32_e64 s[100:101], 15, v158
	v_cmp_lt_i32_e32 vcc, 48, v158
	v_cndmask_b32_e64 v55, v210, v43, s[98:99]
	v_cndmask_b32_e64 v57, v210, v42, s[100:101]
	v_cndmask_b32_e32 v38, v210, v59, vcc
	v_cmp_lt_i32_e64 s[98:99], 47, v158
	v_cmp_lt_i32_e64 s[100:101], 18, v158
	v_cmp_lt_i32_e32 vcc, 17, v158
	v_cndmask_b32_e64 v41, v210, v58, s[98:99]
	v_cndmask_b32_e64 v45, v210, v45, s[100:101]
	v_cndmask_b32_e32 v56, v210, v44, vcc
	v_cmp_lt_i32_e64 s[98:99], 50, v158
	v_cmp_lt_i32_e64 s[100:101], 49, v158
	v_cmp_lt_i32_e32 vcc, 20, v158
	v_cndmask_b32_e64 v36, v210, v61, s[98:99]
	v_cndmask_b32_e64 v40, v210, v60, s[100:101]
	v_cndmask_b32_e32 v43, v210, v47, vcc
	v_cmp_lt_i32_e64 s[98:99], 19, v158
	v_cmp_lt_i32_e64 s[100:101], 52, v158
	v_cmp_lt_i32_e32 vcc, 51, v158
	v_cndmask_b32_e64 v46, v210, v46, s[98:99]
	v_cndmask_b32_e64 v35, v210, v63, s[100:101]
	v_cndmask_b32_e32 v39, v210, v62, vcc
	v_cmp_lt_i32_e32 vcc, 22, v158
	s_nop 1
	v_cndmask_b32_e32 v42, v210, v49, vcc
	v_cmp_lt_i32_e32 vcc, 21, v158
	v_cndmask_b32_e32 v44, v210, v48, vcc
	v_cmp_lt_i32_e32 vcc, 54, v158
	v_max_f32_e32 v48, v42, v42
	s_nop 0
	v_cndmask_b32_e32 v34, v210, v65, vcc
	v_max_f32_e32 v47, v34, v34
	v_min_f32_e32 v47, v48, v47
	v_max3_f32 v48, v47, v76, v68
	v_max3_f32 v47, v47, v72, v66
	v_cmp_lt_i32_e32 vcc, 53, v158
	v_max3_f32 v48, v48, v75, v67
	v_max3_f32 v47, v47, v71, v53
	v_max3_f32 v48, v48, v74, v54
	v_max3_f32 v47, v47, v70, v51
	s_nop 0
	v_cndmask_b32_e32 v37, v210, v64, vcc
	v_max3_f32 v48, v48, v73, v52
	v_max3_f32 v47, v47, v69, v50
	v_max3_f32 v48, v48, v57, v41
	v_max3_f32 v47, v47, v55, v38
	v_max3_f32 v48, v48, v56, v40
	v_max3_f32 v47, v47, v45, v36
	v_max3_f32 v48, v48, v46, v39
	v_max3_f32 v47, v47, v43, v35
	v_max3_f32 v48, v48, v44, v37
	v_max3_f32 v47, v47, v42, v34
	v_max_f32_e32 v47, v47, v47
	v_max_f32_e32 v48, v48, v48
	v_max_f32_e32 v47, v48, v47
	v_mov_b32_e32 v48, v47
	s_nop 1
	v_permlane32_swap_b32_e32 v48, v47
	v_max_f32_e32 v47, v47, v48
	v_cmp_lt_f32_e64 s[26:27], s2, v47
	s_mov_b32 s2, 0x41000000
	v_cmp_lt_f32_e32 vcc, s2, v47
	s_mov_b32 s2, 0xc1000000
	v_cmp_gt_f32_e64 s[2:3], s2, v47
	s_and_b64 s[2:3], s[2:3], s[26:27]
	s_andn2_b64 s[2:3], s[2:3], s[22:23]
	s_or_b64 s[2:3], s[2:3], vcc
	s_and_b64 vcc, exec, s[2:3]
	s_cbranch_vccnz .LBB0_515

; template <int MODE>
; DI void bias_init(f32x16& s0, f32x16& s1, const TP& tp, float fbm, int hi) {
; #pragma unroll
;     for (int r = 0; r < 16; ++r) {
;         const int kvc = 16 * (r >> 3) + (r & 7);
;         if (MODE == 0) { s0[r] = __builtin_fmaf(-L2E, tp.cs[kvc + 8 * hi], fbm); s1[r] = __builtin_fmaf(-L2E, tp.cs[kvc + 32 + 8 * hi], fbm); }
;         else { s0[r] = __builtin_fmaf(tp.sl, (float)kvc, fbm); s1[r] = __builtin_fmaf(tp.sl, (float)(kvc + 32), fbm); }
;     }
; }
; DI float max3_asm(float a, float b, float c) { float r; asm("v_max3_f32 %0, %1, %2, %3" : "=v"(r) : "v"(a), "v"(b), "v"(c)); return r; }
; template <bool MASK>
; DI float mask_rowmax(f32x16& s0, f32x16& s1, const TP& tp) {
;     if (MASK) {
; #pragma unroll
;         for (int r = 0; r < 16; ++r) {
;             const int kvc = 16 * (r >> 3) + (r & 7);
;             const bool v0 = tp.sel && (kvc <= tp.lim) && (kvc > tp.lim2), v1 = tp.sel && (kvc + 32 <= tp.lim) && (kvc + 32 > tp.lim2);
;             s0[r] = v0 ? s0[r] : -1e30f; s1[r] = v1 ? s1[r] : -1e30f;
;         }
;     }
;     const float seed = __builtin_fminf(s0[15], s1[15]);
;     float ma = seed, mb = seed;
; #pragma unroll
;     for (int r = 0; r < 16; r += 2) { ma = max3_asm(ma, s0[r], s1[r]); mb = max3_asm(mb, s0[r + 1], s1[r + 1]); }
;     const float mx = fmaxf(ma, mb);
;     return fmaxf(mx, __shfl_xor(mx, 32));
; }
; template <int MODE, bool MASK, bool WITH_O>
; DI void attn_tile_t(lptr Kt, lptr Vt, const bf16x8 (&qf)[4], f32x16& o0, f32x16& o1, RowState& rs, const TP& tp, int lane) {
;     const int hi = lane >> 5;
;     f32x16 s0, s1;
;     bias_init<MODE>(s0, s1, tp, tp.fb - rs.mref, hi);
;     qk_acc(Kt, qf, s0, s1, lane);
;     const float mx = mask_rowmax<MASK>(s0, s1, tp);
;     const bool was = rs.seen; rs.seen = was || (mx > -1e29f);
;     const bool trig = (mx > 8.f) || (!was && mx > -1e29f && mx < -8.f);
;     if (__builtin_expect(__any(trig), 0)) {
; DI void cmpwin_unit(const Params& P, lptr L, int u, int tid, int lane, int wid) {
;     ...
;         ATT_LOOP_BEGIN(NTC, false, kb_ + (size_t)(jt * 64) * 64, vb_ + (size_t)jt * 64, (const float*)nullptr)
;             const int n0 = jt * 64;
;             TP tp; tp.cs = nullptr; tp.sl = 16.f * sl; tp.fb = sl * (float)(16 * (n0 + 8 * hi) + 31 - t); tp.lim = nlim - n0 - 8 * hi; tp.lim2 = -(1 << 30); tp.sel = true;
.LBB0_526:
	v_cvt_f32_i32_e32 v2, v47
	s_and_b32 s43, s30, 1
	s_mul_i32 s2, s43, 0x2400
	s_add_i32 s52, s2, 0
	v_mul_f32_e32 v50, v150, v2
	s_cmp_gt_i32 s42, s29
	s_mov_b64 s[2:3], -1
	s_cbranch_scc1 .LBB0_535
	s_mov_b32 s2, 2.0
	v_sub_f32_e32 v2, v50, v49
	s_mov_b32 s3, 0x40400000
	v_add3_u32 v51, s52, v131, v133
	v_pk_fma_f32 v[20:21], v[80:81], s[2:3], v[2:3] op_sel_hi:[1,1,0]
	s_mov_b32 s2, 4.0
	ds_read_b128 v[52:55], v51 offset:4608
	ds_read_b128 v[56:59], v51
	ds_read_b128 v[60:63], v51 offset:32
	ds_read_b128 v[64:67], v51 offset:4640
	ds_read_b128 v[68:71], v51 offset:64
	ds_read_b128 v[88:91], v51 offset:4672
	ds_read_b128 v[92:95], v51 offset:96
	ds_read_b128 v[114:117], v51 offset:4704
	s_mov_b32 s3, 0x40a00000
	v_pk_fma_f32 v[22:23], v[80:81], s[2:3], v[2:3] op_sel_hi:[1,1,0]
	s_mov_b32 s2, 0x40c00000
	s_mov_b32 s3, 0x40e00000
	v_pk_fma_f32 v[24:25], v[80:81], s[2:3], v[2:3] op_sel_hi:[1,1,0]
	s_mov_b32 s2, 0x41800000
	s_mov_b32 s3, 0x41880000
	v_pk_fma_f32 v[26:27], v[80:81], s[2:3], v[2:3] op_sel_hi:[1,1,0]
	s_mov_b32 s2, 0x41900000
	s_mov_b32 s3, 0x41980000
	v_pk_fma_f32 v[28:29], v[80:81], s[2:3], v[2:3] op_sel_hi:[1,1,0]
	s_mov_b32 s2, 0x41a00000
	s_mov_b32 s3, 0x41a80000
	v_mov_b32_e32 v79, v78
	v_fma_f32 v18, 0, v78, v2
	v_add_f32_e32 v19, v78, v2
	v_pk_fma_f32 v[30:31], v[80:81], s[2:3], v[2:3] op_sel_hi:[1,1,0]
	v_pk_fma_f32 v[32:33], v[80:81], s[18:19], v[2:3] op_sel_hi:[1,1,0]
	v_pk_fma_f32 v[16:17], v[78:79], s[4:5], v[2:3] op_sel_hi:[1,1,0]
	v_pk_fma_f32 v[14:15], v[78:79], s[14:15], v[2:3] op_sel_hi:[1,1,0]
	v_pk_fma_f32 v[12:13], v[78:79], s[16:17], v[2:3] op_sel_hi:[1,1,0]
	v_pk_fma_f32 v[10:11], v[78:79], s[94:95], v[2:3] op_sel_hi:[1,1,0]
	v_pk_fma_f32 v[8:9], v[78:79], s[96:97], v[2:3] op_sel_hi:[1,1,0]
	v_pk_fma_f32 v[6:7], v[78:79], s[84:85], v[2:3] op_sel_hi:[1,1,0]
	v_pk_fma_f32 v[4:5], v[78:79], s[72:73], v[2:3] op_sel_hi:[1,1,0]
	v_pk_fma_f32 v[2:3], v[82:83], s[44:45], v[2:3] op_sel_hi:[1,1,0]
	s_setprio 1
	s_waitcnt vmcnt(4) lgkmcnt(6)
	v_mfma_f32_32x32x16_bf16 v[18:33], v[56:59], v[98:101], v[18:33]
	v_mfma_f32_32x32x16_bf16 v[2:17], v[52:55], v[98:101], v[2:17]
	s_waitcnt vmcnt(3) lgkmcnt(5)
	v_mfma_f32_32x32x16_bf16 v[18:33], v[60:63], v[102:105], v[18:33]
	s_waitcnt lgkmcnt(4)
	v_mfma_f32_32x32x16_bf16 v[2:17], v[64:67], v[102:105], v[2:17]
	s_waitcnt vmcnt(2) lgkmcnt(3)
	v_mfma_f32_32x32x16_bf16 v[18:33], v[68:71], v[106:109], v[18:33]
	s_waitcnt lgkmcnt(2)
	v_mfma_f32_32x32x16_bf16 v[2:17], v[88:91], v[106:109], v[2:17]
	s_waitcnt vmcnt(1) lgkmcnt(1)
	v_mfma_f32_32x32x16_bf16 v[18:33], v[92:95], v[110:113], v[18:33]
	s_waitcnt lgkmcnt(0)
	v_mfma_f32_32x32x16_bf16 v[2:17], v[114:117], v[110:113], v[2:17]
	s_setprio 0
	s_nop 10
	v_max_f32_e32 v51, v17, v17
	v_max_f32_e32 v52, v33, v33
	v_min_f32_e32 v51, v52, v51
	v_max3_f32 v52, v51, v18, v2
	v_max3_f32 v51, v51, v19, v3
	v_max3_f32 v52, v52, v20, v4
	v_max3_f32 v51, v51, v21, v5
	v_max3_f32 v52, v52, v22, v6
	v_max3_f32 v51, v51, v23, v7
	s_mov_b32 s2, 0xefa18f08
	v_max3_f32 v52, v52, v24, v8
	v_max3_f32 v51, v51, v25, v9
	s_mov_b64 s[26:27], -1
	v_max3_f32 v52, v52, v26, v10
	v_max3_f32 v51, v51, v27, v11
	v_max3_f32 v52, v52, v28, v12
	v_max3_f32 v51, v51, v29, v13
	v_max3_f32 v52, v52, v30, v14
	v_max3_f32 v51, v51, v31, v15
	v_max3_f32 v52, v52, v32, v16
	v_max3_f32 v51, v51, v33, v17
	v_max_f32_e32 v51, v51, v51
	v_max_f32_e32 v52, v52, v52
	v_max_f32_e32 v51, v52, v51
	v_mov_b32_e32 v52, v51
	s_nop 1
	v_permlane32_swap_b32_e32 v52, v51
	v_max_f32_e32 v53, v51, v52
	v_cmp_lt_f32_e64 s[24:25], s2, v53
	s_mov_b32 s2, 0x41000000
	v_cmp_lt_f32_e32 vcc, s2, v53
	s_mov_b32 s26, 0xc1000000
	v_cmp_gt_f32_e64 s[26:27], s26, v53
	s_and_b64 s[26:27], s[26:27], s[24:25]
	s_andn2_b64 s[26:27], s[26:27], s[0:1]
	s_or_b64 s[26:27], s[26:27], vcc
	s_and_b64 vcc, exec, s[26:27]
	v_mov_b32_e32 v51, v49
	v_mov_b32_e32 v52, v46
	s_cbranch_vccnz .LBB0_540

; template <int MODE>
; DI void bias_init(f32x16& s0, f32x16& s1, const TP& tp, float fbm, int hi) {
; #pragma unroll
;     for (int r = 0; r < 16; ++r) {
;         const int kvc = 16 * (r >> 3) + (r & 7);
;         if (MODE == 0) { s0[r] = __builtin_fmaf(-L2E, tp.cs[kvc + 8 * hi], fbm); s1[r] = __builtin_fmaf(-L2E, tp.cs[kvc + 32 + 8 * hi], fbm); }
;         else { s0[r] = __builtin_fmaf(tp.sl, (float)kvc, fbm); s1[r] = __builtin_fmaf(tp.sl, (float)(kvc + 32), fbm); }
;     }
; }
; DI float max3_asm(float a, float b, float c) { float r; asm("v_max3_f32 %0, %1, %2, %3" : "=v"(r) : "v"(a), "v"(b), "v"(c)); return r; }
; template <bool MASK>
; DI float mask_rowmax(f32x16& s0, f32x16& s1, const TP& tp) {
;     if (MASK) {
; #pragma unroll
;         for (int r = 0; r < 16; ++r) {
;             const int kvc = 16 * (r >> 3) + (r & 7);
;             const bool v0 = tp.sel && (kvc <= tp.lim) && (kvc > tp.lim2), v1 = tp.sel && (kvc + 32 <= tp.lim) && (kvc + 32 > tp.lim2);
;             s0[r] = v0 ? s0[r] : -1e30f; s1[r] = v1 ? s1[r] : -1e30f;
;         }
;     }
;     const float seed = __builtin_fminf(s0[15], s1[15]);
;     float ma = seed, mb = seed;
; #pragma unroll
;     for (int r = 0; r < 16; r += 2) { ma = max3_asm(ma, s0[r], s1[r]); mb = max3_asm(mb, s0[r + 1], s1[r + 1]); }
;     const float mx = fmaxf(ma, mb);
;     return fmaxf(mx, __shfl_xor(mx, 32));
; }
; template <int MODE, bool MASK, bool WITH_O>
; DI void attn_tile_t(lptr Kt, lptr Vt, const bf16x8 (&qf)[4], f32x16& o0, f32x16& o1, RowState& rs, const TP& tp, int lane) {
;     const int hi = lane >> 5;
;     f32x16 s0, s1;
;     bias_init<MODE>(s0, s1, tp, tp.fb - rs.mref, hi);
;     qk_acc(Kt, qf, s0, s1, lane);
;     const float mx = mask_rowmax<MASK>(s0, s1, tp);
;     const bool was = rs.seen; rs.seen = was || (mx > -1e29f);
;     const bool trig = (mx > 8.f) || (!was && mx > -1e29f && mx < -8.f);
;     if (__builtin_expect(__any(trig), 0)) {
; DI void cmpwin_unit(const Params& P, lptr L, int u, int tid, int lane, int wid) {
;     ...
;         ATT_LOOP_BEGIN(NTC, false, kb_ + (size_t)(jt * 64) * 64, vb_ + (size_t)jt * 64, (const float*)nullptr)
;             const int n0 = jt * 64;
;             TP tp; tp.cs = nullptr; tp.sl = 16.f * sl; tp.fb = sl * (float)(16 * (n0 + 8 * hi) + 31 - t); tp.lim = nlim - n0 - 8 * hi; tp.lim2 = -(1 << 30); tp.sel = true;
.LBB0_535:
	s_and_b64 vcc, exec, s[2:3]
	s_cbranch_vccz .LBB0_531
	v_sub_f32_e32 v18, v50, v49
	v_add3_u32 v232, s52, v131, v133
	ds_read_b128 v[50:53], v232 offset:4608
	ds_read_b128 v[54:57], v232
	ds_read_b128 v[58:61], v232 offset:32
	ds_read_b128 v[62:65], v232 offset:4640
	ds_read_b128 v[66:69], v232 offset:64
	ds_read_b128 v[70:73], v232 offset:4672
	ds_read_b128 v[88:91], v232 offset:96
	ds_read_b128 v[92:95], v232 offset:4704
	s_mov_b32 s2, 2.0
	v_mov_b32_e32 v79, v78
	s_mov_b32 s3, 0x40400000
	v_pk_fma_f32 v[32:33], v[78:79], s[4:5], v[18:19] op_sel_hi:[1,1,0]
	v_pk_fma_f32 v[30:31], v[78:79], s[14:15], v[18:19] op_sel_hi:[1,1,0]
	v_pk_fma_f32 v[28:29], v[78:79], s[16:17], v[18:19] op_sel_hi:[1,1,0]
	v_pk_fma_f32 v[26:27], v[78:79], s[94:95], v[18:19] op_sel_hi:[1,1,0]
	v_pk_fma_f32 v[24:25], v[78:79], s[96:97], v[18:19] op_sel_hi:[1,1,0]
	v_pk_fma_f32 v[22:23], v[78:79], s[84:85], v[18:19] op_sel_hi:[1,1,0]
	v_pk_fma_f32 v[20:21], v[78:79], s[72:73], v[18:19] op_sel_hi:[1,1,0]
	v_pk_fma_f32 v[4:5], v[80:81], s[2:3], v[18:19] op_sel_hi:[1,1,0]
	s_mov_b32 s2, 4.0
	s_mov_b32 s3, 0x40a00000
	v_pk_fma_f32 v[6:7], v[80:81], s[2:3], v[18:19] op_sel_hi:[1,1,0]
	s_mov_b32 s2, 0x40c00000
	s_mov_b32 s3, 0x40e00000
	v_pk_fma_f32 v[8:9], v[80:81], s[2:3], v[18:19] op_sel_hi:[1,1,0]
	s_mov_b32 s2, 0x41800000
	s_mov_b32 s3, 0x41880000
	v_pk_fma_f32 v[10:11], v[80:81], s[2:3], v[18:19] op_sel_hi:[1,1,0]
	s_mov_b32 s2, 0x41900000
	s_mov_b32 s3, 0x41980000
	v_pk_fma_f32 v[12:13], v[80:81], s[2:3], v[18:19] op_sel_hi:[1,1,0]
	s_mov_b32 s2, 0x41a00000
	s_mov_b32 s3, 0x41a80000
	v_fma_f32 v2, 0, v78, v18
	v_add_f32_e32 v3, v78, v18
	v_pk_fma_f32 v[14:15], v[80:81], s[2:3], v[18:19] op_sel_hi:[1,1,0]
	v_pk_fma_f32 v[16:17], v[80:81], s[18:19], v[18:19] op_sel_hi:[1,1,0]
	v_pk_fma_f32 v[18:19], v[82:83], s[44:45], v[18:19] op_sel_hi:[1,1,0]
	s_setprio 1
	s_waitcnt vmcnt(4) lgkmcnt(6)
	v_mfma_f32_32x32x16_bf16 v[2:17], v[54:57], v[98:101], v[2:17]
	v_mfma_f32_32x32x16_bf16 v[18:33], v[50:53], v[98:101], v[18:33]
	s_waitcnt vmcnt(3) lgkmcnt(5)
	v_mfma_f32_32x32x16_bf16 v[2:17], v[58:61], v[102:105], v[2:17]
	s_waitcnt lgkmcnt(4)
	v_mfma_f32_32x32x16_bf16 v[18:33], v[62:65], v[102:105], v[18:33]
	s_waitcnt vmcnt(2) lgkmcnt(3)
	v_mfma_f32_32x32x16_bf16 v[2:17], v[66:69], v[106:109], v[2:17]
	s_waitcnt lgkmcnt(2)
	v_mfma_f32_32x32x16_bf16 v[18:33], v[70:73], v[106:109], v[18:33]
	s_waitcnt vmcnt(1) lgkmcnt(1)
	v_mfma_f32_32x32x16_bf16 v[2:17], v[88:91], v[110:113], v[2:17]
	s_waitcnt lgkmcnt(0)
	v_mfma_f32_32x32x16_bf16 v[18:33], v[92:95], v[110:113], v[18:33]
	s_setprio 0
	v_cmp_lt_i32_e32 vcc, 0, v48
	s_mov_b32 s2, 0xefa18f08
	s_nop 6
	v_cndmask_b32_e32 v51, v210, v3, vcc
	v_cmp_lt_i32_e64 s[98:99], -1, v48
	v_cmp_lt_i32_e64 s[100:101], 32, v48
	v_cmp_lt_i32_e32 vcc, 31, v48
	v_cndmask_b32_e64 v55, v210, v2, s[98:99]
	v_cndmask_b32_e64 v53, v210, v19, s[100:101]
	v_cndmask_b32_e32 v58, v210, v18, vcc
	v_cmp_lt_i32_e64 s[98:99], 2, v48
	v_cmp_lt_i32_e64 s[100:101], 1, v48
	v_cmp_lt_i32_e32 vcc, 34, v48
	v_cndmask_b32_e64 v50, v210, v5, s[98:99]
	v_cndmask_b32_e64 v57, v210, v4, s[100:101]
	v_cndmask_b32_e32 v21, v210, v21, vcc
	v_cmp_lt_i32_e64 s[98:99], 33, v48
	v_cmp_lt_i32_e64 s[100:101], 4, v48
	v_cmp_lt_i32_e32 vcc, 3, v48
	v_cndmask_b32_e64 v59, v210, v20, s[98:99]
	v_cndmask_b32_e64 v18, v210, v7, s[100:101]
	v_cndmask_b32_e32 v54, v210, v6, vcc
	v_cmp_lt_i32_e64 s[98:99], 36, v48
	v_cmp_lt_i32_e64 s[100:101], 35, v48
	v_cmp_lt_i32_e32 vcc, 6, v48
	v_cndmask_b32_e64 v20, v210, v23, s[98:99]
	v_cndmask_b32_e64 v56, v210, v22, s[100:101]
	v_cndmask_b32_e32 v9, v210, v9, vcc
	v_cmp_lt_i32_e64 s[98:99], 5, v48
	v_cmp_lt_i32_e64 s[100:101], 38, v48
	v_cmp_lt_i32_e32 vcc, 37, v48
	v_cndmask_b32_e64 v52, v210, v8, s[98:99]
	v_cndmask_b32_e64 v19, v210, v25, s[100:101]
	v_cndmask_b32_e32 v25, v210, v24, vcc
	v_cmp_lt_i32_e64 s[98:99], 16, v48
	v_cmp_lt_i32_e64 s[100:101], 15, v48
	v_cmp_lt_i32_e32 vcc, 48, v48
	v_cndmask_b32_e64 v6, v210, v11, s[98:99]
	v_cndmask_b32_e64 v22, v210, v10, s[100:101]
	v_cndmask_b32_e32 v8, v210, v27, vcc
	v_cmp_lt_i32_e32 vcc, 47, v48
	s_nop 1
	v_cndmask_b32_e32 v24, v210, v26, vcc
	v_cmp_lt_i32_e32 vcc, 18, v48
	v_cndmask_b32_e32 v4, v210, v13, vcc
	v_cmp_lt_i32_e64 s[98:99], 17, v48
	v_cmp_lt_i32_e64 s[100:101], 50, v48
	v_cmp_lt_i32_e32 vcc, 49, v48
	v_cndmask_b32_e64 v13, v210, v12, s[98:99]
	v_cndmask_b32_e64 v7, v210, v29, s[100:101]
	v_cndmask_b32_e32 v23, v210, v28, vcc
	v_cmp_lt_i32_e64 s[98:99], 20, v48
	v_cmp_lt_i32_e64 s[100:101], 19, v48
	v_cmp_lt_i32_e32 vcc, 52, v48
	v_cndmask_b32_e64 v3, v210, v15, s[98:99]
	v_cndmask_b32_e64 v11, v210, v14, s[100:101]
	v_cndmask_b32_e32 v5, v210, v31, vcc
	v_cmp_lt_i32_e64 s[98:99], 51, v48
	v_cmp_lt_i32_e64 s[100:101], 22, v48
	v_cmp_lt_i32_e32 vcc, 21, v48
	v_cndmask_b32_e64 v14, v210, v30, s[98:99]
	v_cndmask_b32_e64 v2, v210, v17, s[100:101]
	v_cndmask_b32_e32 v10, v210, v16, vcc
	v_cmp_lt_i32_e32 vcc, 54, v48
	v_max_f32_e32 v16, v2, v2
	s_nop 0
	v_cndmask_b32_e32 v17, v210, v33, vcc
	v_max_f32_e32 v15, v17, v17
	v_min_f32_e32 v15, v16, v15
	v_max3_f32 v16, v15, v55, v58
	v_max3_f32 v15, v15, v51, v53
	v_cmp_lt_i32_e32 vcc, 53, v48
	v_max3_f32 v16, v16, v57, v59
	v_max3_f32 v15, v15, v50, v21
	v_max3_f32 v16, v16, v54, v56
	v_max3_f32 v15, v15, v18, v20
	s_nop 0
	v_cndmask_b32_e32 v12, v210, v32, vcc
	v_max3_f32 v16, v16, v52, v25
	v_max3_f32 v15, v15, v9, v19
	v_max3_f32 v16, v16, v22, v24
	v_max3_f32 v15, v15, v6, v8
	v_max3_f32 v16, v16, v13, v23
	v_max3_f32 v15, v15, v4, v7
	v_max3_f32 v16, v16, v11, v14
	v_max3_f32 v15, v15, v3, v5
	v_max3_f32 v16, v16, v10, v12
	v_max3_f32 v15, v15, v2, v17
	v_max_f32_e32 v15, v15, v15
	v_max_f32_e32 v16, v16, v16
	v_max_f32_e32 v15, v16, v15
	v_mov_b32_e32 v16, v15
	s_nop 1
	v_permlane32_swap_b32_e32 v16, v15
	v_max_f32_e32 v15, v15, v16
	v_cmp_lt_f32_e64 s[24:25], s2, v15
	s_mov_b32 s2, 0x41000000
	v_cmp_lt_f32_e32 vcc, s2, v15
	s_mov_b32 s2, 0xc1000000
	v_cmp_gt_f32_e64 s[2:3], s2, v15
	s_and_b64 s[2:3], s[2:3], s[24:25]
	s_andn2_b64 s[2:3], s[2:3], s[0:1]
	s_or_b64 s[2:3], s[2:3], vcc
	s_and_b64 vcc, exec, s[2:3]
	s_cbranch_vccnz .LBB0_541

; template <int MODE>
; DI void bias_init(f32x16& s0, f32x16& s1, const TP& tp, float fbm, int hi) {
; #pragma unroll
;     for (int r = 0; r < 16; ++r) {
;         const int kvc = 16 * (r >> 3) + (r & 7);
;         if (MODE == 0) { s0[r] = __builtin_fmaf(-L2E, tp.cs[kvc + 8 * hi], fbm); s1[r] = __builtin_fmaf(-L2E, tp.cs[kvc + 32 + 8 * hi], fbm); }
;         else { s0[r] = __builtin_fmaf(tp.sl, (float)kvc, fbm); s1[r] = __builtin_fmaf(tp.sl, (float)(kvc + 32), fbm); }
;     }
; }
; DI float max3_asm(float a, float b, float c) { float r; asm("v_max3_f32 %0, %1, %2, %3" : "=v"(r) : "v"(a), "v"(b), "v"(c)); return r; }
; template <bool MASK>
; DI float mask_rowmax(f32x16& s0, f32x16& s1, const TP& tp) {
;     if (MASK) {
; #pragma unroll
;         for (int r = 0; r < 16; ++r) {
;             const int kvc = 16 * (r >> 3) + (r & 7);
;             const bool v0 = tp.sel && (kvc <= tp.lim) && (kvc > tp.lim2), v1 = tp.sel && (kvc + 32 <= tp.lim) && (kvc + 32 > tp.lim2);
;             s0[r] = v0 ? s0[r] : -1e30f; s1[r] = v1 ? s1[r] : -1e30f;
;         }
;     }
;     const float seed = __builtin_fminf(s0[15], s1[15]);
;     float ma = seed, mb = seed;
; #pragma unroll
;     for (int r = 0; r < 16; r += 2) { ma = max3_asm(ma, s0[r], s1[r]); mb = max3_asm(mb, s0[r + 1], s1[r + 1]); }
;     const float mx = fmaxf(ma, mb);
;     return fmaxf(mx, __shfl_xor(mx, 32));
; }
; template <int MODE, bool MASK, bool WITH_O>
; DI void attn_tile_t(lptr Kt, lptr Vt, const bf16x8 (&qf)[4], f32x16& o0, f32x16& o1, RowState& rs, const TP& tp, int lane) {
;     const int hi = lane >> 5;
;     f32x16 s0, s1;
;     bias_init<MODE>(s0, s1, tp, tp.fb - rs.mref, hi);
;     qk_acc(Kt, qf, s0, s1, lane);
;     const float mx = mask_rowmax<MASK>(s0, s1, tp);
;     const bool was = rs.seen; rs.seen = was || (mx > -1e29f);
;     const bool trig = (mx > 8.f) || (!was && mx > -1e29f && mx < -8.f);
;     if (__builtin_expect(__any(trig), 0)) {
; DI void cmpwin_unit(const Params& P, lptr L, int u, int tid, int lane, int wid) {
;     ...
;             const int kv0 = (jw0 + jt) * 64;
;             TP tp; tp.cs = nullptr; tp.sl = sl; tp.fb = sl * (float)(kv0 + 8 * hi - t); tp.lim = t - kv0 - 8 * hi; tp.lim2 = tp.lim - 512; tp.sel = true;
;             const bool full = (kv0 + 63 <= tq0) && (tq0 + 31 - kv0 < 512);
;             attn_tile<1>(Kt, Vt, qf, o0, o1, rs, tp, !full, lane);
.LBB0_581:
	s_and_b32 s54, s53, 1
	s_mul_i32 s2, s54, 0x2400
	v_add_u32_e32 v34, s43, v161
	s_add_i32 s55, s2, 0
	s_add_i32 s2, s43, 63
	v_cvt_f32_i32_e32 v34, v34
	s_cmp_gt_u32 s2, s81
	s_cselect_b64 s[2:3], -1, 0
	s_cmp_lt_i32 s43, s23
	s_cselect_b64 s[28:29], -1, 0
	s_or_b64 s[2:3], s[2:3], s[28:29]
	v_mul_f32_e32 v216, v150, v34
	s_andn2_b64 vcc, exec, s[2:3]
	s_mov_b64 s[2:3], -1
	s_cbranch_vccz .LBB0_590
	v_add3_u32 v234, s55, v131, v133
	ds_read_b128 v[34:37], v234 offset:4608
	ds_read_b128 v[38:41], v234
	ds_read_b128 v[42:45], v234 offset:32
	ds_read_b128 v[46:49], v234 offset:4640
	ds_read_b128 v[50:53], v234 offset:64
	ds_read_b128 v[54:57], v234 offset:4672
	ds_read_b128 v[58:61], v234 offset:96
	ds_read_b128 v[62:65], v234 offset:4704
	s_mov_b32 s2, 2.0
	v_sub_f32_e32 v232, v216, v215
	s_mov_b32 s3, 0x40400000
	v_pk_fma_f32 v[84:85], v[166:167], s[2:3], v[232:233] op_sel_hi:[1,1,0]
	s_mov_b32 s2, 4.0
	s_mov_b32 s3, 0x40a00000
	v_pk_fma_f32 v[86:87], v[166:167], s[2:3], v[232:233] op_sel_hi:[1,1,0]
	s_mov_b32 s2, 0x40c00000
	s_mov_b32 s3, 0x40e00000
	v_pk_fma_f32 v[88:89], v[166:167], s[2:3], v[232:233] op_sel_hi:[1,1,0]
	s_mov_b32 s2, 0x41800000
	s_mov_b32 s3, 0x41880000
	v_pk_fma_f32 v[90:91], v[166:167], s[2:3], v[232:233] op_sel_hi:[1,1,0]
	s_mov_b32 s2, 0x41900000
	s_mov_b32 s3, 0x41980000
	v_pk_fma_f32 v[92:93], v[166:167], s[2:3], v[232:233] op_sel_hi:[1,1,0]
	s_mov_b32 s2, 0x41a00000
	s_mov_b32 s3, 0x41a80000
	v_mov_b32_e32 v151, v150
	v_fma_f32 v82, 0, v150, v232
	v_add_f32_e32 v83, v150, v232
	v_pk_fma_f32 v[94:95], v[166:167], s[2:3], v[232:233] op_sel_hi:[1,1,0]
	v_pk_fma_f32 v[96:97], v[166:167], s[18:19], v[232:233] op_sel_hi:[1,1,0]
	v_pk_fma_f32 v[80:81], v[150:151], s[4:5], v[232:233] op_sel_hi:[1,1,0]
	v_pk_fma_f32 v[78:79], v[150:151], s[14:15], v[232:233] op_sel_hi:[1,1,0]
	v_pk_fma_f32 v[76:77], v[150:151], s[16:17], v[232:233] op_sel_hi:[1,1,0]
	v_pk_fma_f32 v[74:75], v[150:151], s[94:95], v[232:233] op_sel_hi:[1,1,0]
	v_pk_fma_f32 v[72:73], v[150:151], s[96:97], v[232:233] op_sel_hi:[1,1,0]
	v_pk_fma_f32 v[70:71], v[150:151], s[84:85], v[232:233] op_sel_hi:[1,1,0]
	v_pk_fma_f32 v[68:69], v[150:151], s[72:73], v[232:233] op_sel_hi:[1,1,0]
	v_pk_fma_f32 v[66:67], v[168:169], s[44:45], v[232:233] op_sel_hi:[1,1,0]
	s_setprio 1
	s_waitcnt lgkmcnt(6)
	v_mfma_f32_32x32x16_bf16 v[82:97], v[38:41], v[98:101], v[82:97]
	v_mfma_f32_32x32x16_bf16 v[66:81], v[34:37], v[98:101], v[66:81]
	s_waitcnt lgkmcnt(5)
	v_mfma_f32_32x32x16_bf16 v[82:97], v[42:45], v[102:105], v[82:97]
	s_waitcnt lgkmcnt(4)
	v_mfma_f32_32x32x16_bf16 v[66:81], v[46:49], v[102:105], v[66:81]
	s_waitcnt lgkmcnt(3)
	v_mfma_f32_32x32x16_bf16 v[82:97], v[50:53], v[106:109], v[82:97]
	s_waitcnt lgkmcnt(2)
	v_mfma_f32_32x32x16_bf16 v[66:81], v[54:57], v[106:109], v[66:81]
	s_waitcnt lgkmcnt(1)
	v_mfma_f32_32x32x16_bf16 v[82:97], v[58:61], v[110:113], v[82:97]
	s_waitcnt lgkmcnt(0)
	v_mfma_f32_32x32x16_bf16 v[66:81], v[62:65], v[110:113], v[66:81]
	s_setprio 0
	s_nop 10
	v_max_f32_e32 v34, v81, v81
	v_max_f32_e32 v35, v97, v97
	v_min_f32_e32 v34, v35, v34
	v_max3_f32 v35, v34, v82, v66
	v_max3_f32 v34, v34, v83, v67
	s_mov_b32 s2, 0xefa18f08
	v_max3_f32 v35, v35, v84, v68
	v_max3_f32 v34, v34, v85, v69
	s_mov_b64 s[30:31], -1
	v_max3_f32 v35, v35, v86, v70
	v_max3_f32 v34, v34, v87, v71
	v_max3_f32 v35, v35, v88, v72
	v_max3_f32 v34, v34, v89, v73
	v_max3_f32 v35, v35, v90, v74
	v_max3_f32 v34, v34, v91, v75
	v_max3_f32 v35, v35, v92, v76
	v_max3_f32 v34, v34, v93, v77
	v_max3_f32 v35, v35, v94, v78
	v_max3_f32 v34, v34, v95, v79
	v_max3_f32 v35, v35, v96, v80
	v_max3_f32 v34, v34, v97, v81
	v_max_f32_e32 v34, v34, v34
	v_max_f32_e32 v35, v35, v35
	v_max_f32_e32 v34, v35, v34
	v_mov_b32_e32 v35, v34
	s_nop 1
	v_permlane32_swap_b32_e32 v35, v34
	v_max_f32_e32 v218, v34, v35
	v_cmp_lt_f32_e64 s[28:29], s2, v218
	s_mov_b32 s2, 0x41000000
	v_cmp_lt_f32_e32 vcc, s2, v218
	s_mov_b32 s30, 0xc1000000
	v_cmp_gt_f32_e64 s[30:31], s30, v218
	s_and_b64 s[30:31], s[30:31], s[28:29]
	s_andn2_b64 s[30:31], s[30:31], s[24:25]
	s_or_b64 s[30:31], s[30:31], vcc
	s_and_b64 vcc, exec, s[30:31]
	v_mov_b32_e32 v217, v163
	v_mov_b32_e32 v151, v215
	s_cbranch_vccnz .LBB0_595

; DI void qk_acc(lptr Kt, const bf16x8 (&qf)[4], f32x16& s0, f32x16& s1, int lane) {
;     const int i = lane & 31, hi = lane >> 5;
;     const int krow = (i & 19) | ((i & 4) << 1) | ((i & 8) >> 1);
;     lptr kp = Kt + krow * KPB + hi * 16;
;     bf16x8 a0[4], a1[4];
; #pragma unroll
;     for (int d0 = 0; d0 < 4; ++d0) { a0[d0] = *(LAS bf16x8*)(kp + d0 * 32); a1[d0] = *(LAS bf16x8*)(kp + 32 * KPB + d0 * 32); }
;     __builtin_amdgcn_s_setprio(1);
; #pragma unroll
;     for (int d0 = 0; d0 < 4; ++d0) { s0 = MFMA32(a0[d0], qf[d0], s0); s1 = MFMA32(a1[d0], qf[d0], s1); }
;     __builtin_amdgcn_s_setprio(0);
; }
; DI bf16x8 pack8(const f32x16& p, int base) {
;     u32x4 w; w.x = pk_bf16(p[base + 0], p[base + 1]); w.y = pk_bf16(p[base + 2], p[base + 3]); w.z = pk_bf16(p[base + 4], p[base + 5]); w.w = pk_bf16(p[base + 6], p[base + 7]);
;     return __builtin_bit_cast(bf16x8, w);
; }
; DI void pv_tile(lptr Vt, const f32x16& p0, const f32x16& p1, f32x16& o0, f32x16& o1, int lane) {
;     const int i = lane & 31, hi = lane >> 5;
;     lptr vp = Vt + i * KPB + hi * 16;
;     {
;         const bf16x8 pf = pack8(p0, 0); const bf16x8 v0 = *(LAS bf16x8*)(vp + 0), v1 = *(LAS bf16x8*)(vp + 32 * KPB + 0);
;         o0 = MFMA32(v0, pf, o0); o1 = MFMA32(v1, pf, o1);
;     }
;     {
;         const bf16x8 pf = pack8(p0, 8); const bf16x8 v0 = *(LAS bf16x8*)(vp + 32), v1 = *(LAS bf16x8*)(vp + 32 * KPB + 32);
;         o0 = MFMA32(v0, pf, o0); o1 = MFMA32(v1, pf, o1);
;     }
;     {
;         const bf16x8 pf = pack8(p1, 0); const bf16x8 v0 = *(LAS bf16x8*)(vp + 64), v1 = *(LAS bf16x8*)(vp + 32 * KPB + 64);
;         o0 = MFMA32(v0, pf, o0); o1 = MFMA32(v1, pf, o1);
;     }
;     {
;         const bf16x8 pf = pack8(p1, 8); const bf16x8 v0 = *(LAS bf16x8*)(vp + 96), v1 = *(LAS bf16x8*)(vp + 32 * KPB + 96);
;         o0 = MFMA32(v0, pf, o0); o1 = MFMA32(v1, pf, o1);
;     }
; }
; template <int MODE>
; DI void bias_init(f32x16& s0, f32x16& s1, const TP& tp, float fbm, int hi) {
; #pragma unroll
;     for (int r = 0; r < 16; ++r) {
;         const int kvc = 16 * (r >> 3) + (r & 7);
;         if (MODE == 0) { s0[r] = __builtin_fmaf(-L2E, tp.cs[kvc + 8 * hi], fbm); s1[r] = __builtin_fmaf(-L2E, tp.cs[kvc + 32 + 8 * hi], fbm); }
;         else { s0[r] = __builtin_fmaf(tp.sl, (float)kvc, fbm); s1[r] = __builtin_fmaf(tp.sl, (float)(kvc + 32), fbm); }
;     }
; }
.LBB0_590:
	s_and_b64 vcc, exec, s[2:3]
	s_cbranch_vccz .LBB0_586
	s_mov_b32 s2, 2.0
	v_sub_f32_e32 v50, v216, v215
	s_mov_b32 s3, 0x40400000
	v_add3_u32 v94, s55, v131, v133
	v_pk_fma_f32 v[36:37], v[166:167], s[2:3], v[50:51] op_sel_hi:[1,1,0]
	s_mov_b32 s2, 4.0
	ds_read_b128 v[66:69], v94 offset:4608
	ds_read_b128 v[70:73], v94
	ds_read_b128 v[74:77], v94 offset:32
	ds_read_b128 v[78:81], v94 offset:4640
	ds_read_b128 v[82:85], v94 offset:64
	ds_read_b128 v[86:89], v94 offset:4672
	ds_read_b128 v[90:93], v94 offset:96
	ds_read_b128 v[94:97], v94 offset:4704
	s_mov_b32 s3, 0x40a00000
	v_pk_fma_f32 v[38:39], v[166:167], s[2:3], v[50:51] op_sel_hi:[1,1,0]
	s_mov_b32 s2, 0x40c00000
	s_mov_b32 s3, 0x40e00000
	v_pk_fma_f32 v[40:41], v[166:167], s[2:3], v[50:51] op_sel_hi:[1,1,0]
	s_mov_b32 s2, 0x41800000
	s_mov_b32 s3, 0x41880000
	v_pk_fma_f32 v[42:43], v[166:167], s[2:3], v[50:51] op_sel_hi:[1,1,0]
	s_mov_b32 s2, 0x41900000
	s_mov_b32 s3, 0x41980000
	v_pk_fma_f32 v[44:45], v[166:167], s[2:3], v[50:51] op_sel_hi:[1,1,0]
	s_mov_b32 s2, 0x41a00000
	s_mov_b32 s3, 0x41a80000
	v_mov_b32_e32 v151, v150
	v_fma_f32 v34, 0, v150, v50
	v_add_f32_e32 v35, v150, v50
	v_pk_fma_f32 v[46:47], v[166:167], s[2:3], v[50:51] op_sel_hi:[1,1,0]
	v_pk_fma_f32 v[48:49], v[166:167], s[18:19], v[50:51] op_sel_hi:[1,1,0]
	v_pk_fma_f32 v[64:65], v[150:151], s[4:5], v[50:51] op_sel_hi:[1,1,0]
	v_pk_fma_f32 v[62:63], v[150:151], s[14:15], v[50:51] op_sel_hi:[1,1,0]
	v_pk_fma_f32 v[60:61], v[150:151], s[16:17], v[50:51] op_sel_hi:[1,1,0]
	v_pk_fma_f32 v[58:59], v[150:151], s[94:95], v[50:51] op_sel_hi:[1,1,0]
	v_pk_fma_f32 v[56:57], v[150:151], s[96:97], v[50:51] op_sel_hi:[1,1,0]
	v_pk_fma_f32 v[54:55], v[150:151], s[84:85], v[50:51] op_sel_hi:[1,1,0]
	v_pk_fma_f32 v[52:53], v[150:151], s[72:73], v[50:51] op_sel_hi:[1,1,0]
	v_pk_fma_f32 v[50:51], v[168:169], s[44:45], v[50:51] op_sel_hi:[1,1,0]
	s_setprio 1
	s_waitcnt lgkmcnt(6)
	v_mfma_f32_32x32x16_bf16 v[34:49], v[70:73], v[98:101], v[34:49]
	v_mfma_f32_32x32x16_bf16 v[50:65], v[66:69], v[98:101], v[50:65]
	s_waitcnt lgkmcnt(5)
	v_mfma_f32_32x32x16_bf16 v[34:49], v[74:77], v[102:105], v[34:49]
	s_waitcnt lgkmcnt(4)
	v_mfma_f32_32x32x16_bf16 v[50:65], v[78:81], v[102:105], v[50:65]
	s_waitcnt lgkmcnt(3)
	v_mfma_f32_32x32x16_bf16 v[34:49], v[82:85], v[106:109], v[34:49]
	s_waitcnt lgkmcnt(2)
	v_mfma_f32_32x32x16_bf16 v[50:65], v[86:89], v[106:109], v[50:65]
	s_waitcnt lgkmcnt(1)
	v_mfma_f32_32x32x16_bf16 v[34:49], v[90:93], v[110:113], v[34:49]
	s_waitcnt lgkmcnt(0)
; DI float max3_asm(float a, float b, float c) { float r; asm("v_max3_f32 %0, %1, %2, %3" : "=v"(r) : "v"(a), "v"(b), "v"(c)); return r; }
; template <bool MASK>
; DI float mask_rowmax(f32x16& s0, f32x16& s1, const TP& tp) {
;     if (MASK) {
; #pragma unroll
;         for (int r = 0; r < 16; ++r) {
;             const int kvc = 16 * (r >> 3) + (r & 7);
;             const bool v0 = tp.sel && (kvc <= tp.lim) && (kvc > tp.lim2), v1 = tp.sel && (kvc + 32 <= tp.lim) && (kvc + 32 > tp.lim2);
;             s0[r] = v0 ? s0[r] : -1e30f; s1[r] = v1 ? s1[r] : -1e30f;
;         }
;     }
;     const float seed = __builtin_fminf(s0[15], s1[15]);
;     float ma = seed, mb = seed;
; #pragma unroll
;     for (int r = 0; r < 16; r += 2) { ma = max3_asm(ma, s0[r], s1[r]); mb = max3_asm(mb, s0[r + 1], s1[r + 1]); }
;     const float mx = fmaxf(ma, mb);
;     return fmaxf(mx, __shfl_xor(mx, 32));
; }
; template <int MODE, bool MASK, bool WITH_O>
; DI void attn_tile_t(lptr Kt, lptr Vt, const bf16x8 (&qf)[4], f32x16& o0, f32x16& o1, RowState& rs, const TP& tp, int lane) {
;     const int hi = lane >> 5;
;     f32x16 s0, s1;
;     bias_init<MODE>(s0, s1, tp, tp.fb - rs.mref, hi);
;     qk_acc(Kt, qf, s0, s1, lane);
;     const float mx = mask_rowmax<MASK>(s0, s1, tp);
;     const bool was = rs.seen; rs.seen = was || (mx > -1e29f);
;     const bool trig = (mx > 8.f) || (!was && mx > -1e29f && mx < -8.f);
;     if (__builtin_expect(__any(trig), 0)) {
	v_mfma_f32_32x32x16_bf16 v[50:65], v[94:97], v[110:113], v[50:65]
	s_setprio 0
	v_add_u32_e32 v66, -1, v155
	v_cmp_gt_u32_e32 vcc, s10, v66
	s_mov_b32 s2, 0xefa18f08
	s_nop 5
	v_cndmask_b32_e32 v68, v210, v35, vcc
	v_cmp_gt_u32_e32 vcc, s10, v155
	v_subrev_u32_e32 v35, 32, v155
	s_nop 0
	v_cndmask_b32_e32 v75, v210, v34, vcc
	v_subrev_u32_e32 v34, 33, v155
	v_cmp_gt_u32_e32 vcc, s10, v34
	v_add_u32_e32 v34, -3, v155
	s_nop 0
	v_cndmask_b32_e32 v51, v210, v51, vcc
	v_cmp_gt_u32_e32 vcc, s10, v35
	v_add_u32_e32 v35, -2, v155
	s_nop 0
	v_cndmask_b32_e32 v67, v210, v50, vcc
	v_cmp_gt_u32_e32 vcc, s10, v34
	v_subrev_u32_e32 v34, 35, v155
	s_nop 0
	v_cndmask_b32_e32 v69, v210, v37, vcc
	v_cmp_gt_u32_e32 vcc, s10, v35
	v_subrev_u32_e32 v35, 34, v155
	v_subrev_u32_e32 v37, 20, v155
	v_cndmask_b32_e32 v72, v210, v36, vcc
	v_cmp_gt_u32_e32 vcc, s10, v34
	v_add_u32_e32 v34, -5, v155
	v_subrev_u32_e32 v36, 48, v155
	v_cndmask_b32_e32 v50, v210, v53, vcc
	v_cmp_gt_u32_e32 vcc, s10, v35
	v_add_u32_e32 v35, -4, v155
	s_nop 0
	v_cndmask_b32_e32 v66, v210, v52, vcc
	v_cmp_gt_u32_e32 vcc, s10, v34
	v_subrev_u32_e32 v34, 37, v155
	s_nop 0
	v_cndmask_b32_e32 v70, v210, v39, vcc
	v_cmp_gt_u32_e32 vcc, s10, v35
	v_subrev_u32_e32 v35, 36, v155
	s_nop 0
	v_cndmask_b32_e32 v73, v210, v38, vcc
	v_cmp_gt_u32_e32 vcc, s10, v34
	v_add_u32_e32 v34, -7, v155
	s_nop 0
	v_cndmask_b32_e32 v52, v210, v55, vcc
	v_cmp_gt_u32_e32 vcc, s10, v35
	v_add_u32_e32 v35, -6, v155
	s_nop 0
	v_cndmask_b32_e32 v54, v210, v54, vcc
	v_cmp_gt_u32_e32 vcc, s10, v34
	v_subrev_u32_e32 v34, 39, v155
	s_nop 0
	v_cndmask_b32_e32 v71, v210, v41, vcc
	v_cmp_gt_u32_e32 vcc, s10, v35
	v_subrev_u32_e32 v35, 38, v155
	s_nop 0
	v_cndmask_b32_e32 v74, v210, v40, vcc
	v_cmp_gt_u32_e32 vcc, s10, v34
	v_add_u32_e32 v34, -16, v155
	v_subrev_u32_e32 v40, 22, v155
	v_cndmask_b32_e32 v53, v210, v57, vcc
	v_cmp_gt_u32_e32 vcc, s10, v35
	v_subrev_u32_e32 v35, 17, v155
	s_nop 0
	v_cndmask_b32_e32 v55, v210, v56, vcc
	v_cmp_gt_u32_e32 vcc, s10, v35
	s_nop 1
	v_cndmask_b32_e32 v43, v210, v43, vcc
	v_cmp_gt_u32_e32 vcc, s10, v34
	v_subrev_u32_e32 v34, 49, v155
	s_nop 0
	v_cndmask_b32_e32 v57, v210, v42, vcc
	v_cmp_gt_u32_e32 vcc, s10, v34
	v_subrev_u32_e32 v34, 19, v155
	s_nop 0
	v_cndmask_b32_e32 v35, v210, v59, vcc
	v_cmp_gt_u32_e32 vcc, s10, v36
	v_subrev_u32_e32 v36, 18, v155
	s_nop 0
	v_cndmask_b32_e32 v41, v210, v58, vcc
	v_cmp_gt_u32_e32 vcc, s10, v34
	v_subrev_u32_e32 v34, 51, v155
	s_nop 0
	v_cndmask_b32_e32 v42, v210, v45, vcc
	v_cmp_gt_u32_e32 vcc, s10, v36
	v_subrev_u32_e32 v36, 50, v155
	s_nop 0
	v_cndmask_b32_e32 v56, v210, v44, vcc
	v_cmp_gt_u32_e32 vcc, s10, v34
	s_nop 1
	v_cndmask_b32_e32 v34, v210, v61, vcc
	v_cmp_gt_u32_e32 vcc, s10, v36
	v_subrev_u32_e32 v36, 21, v155
	s_nop 0
	v_cndmask_b32_e32 v38, v210, v60, vcc
	v_cmp_gt_u32_e32 vcc, s10, v36
	v_subrev_u32_e32 v36, 53, v155
	s_nop 0
	v_cndmask_b32_e32 v44, v210, v47, vcc
	v_cmp_gt_u32_e32 vcc, s10, v37
	v_subrev_u32_e32 v37, 52, v155
	s_nop 0
	v_cndmask_b32_e32 v46, v210, v46, vcc
	v_cmp_gt_u32_e32 vcc, s10, v36
	s_nop 1
	v_cndmask_b32_e32 v36, v210, v63, vcc
	v_cmp_gt_u32_e32 vcc, s10, v37
	v_subrev_u32_e32 v37, 23, v155
	s_nop 0
	v_cndmask_b32_e32 v39, v210, v62, vcc
	v_cmp_gt_u32_e32 vcc, s10, v37
	v_subrev_u32_e32 v37, 55, v155
	s_nop 0
	v_cndmask_b32_e32 v45, v210, v49, vcc
	v_cmp_gt_u32_e32 vcc, s10, v40
	v_max_f32_e32 v49, v45, v45
	v_subrev_u32_e32 v40, 54, v155
	v_cndmask_b32_e32 v47, v210, v48, vcc
	v_cmp_gt_u32_e32 vcc, s10, v37
	s_nop 1
	v_cndmask_b32_e32 v37, v210, v65, vcc
	v_max_f32_e32 v48, v37, v37
	v_min_f32_e32 v48, v49, v48
	v_max3_f32 v49, v48, v75, v67
	v_max3_f32 v48, v48, v68, v51
	v_cmp_gt_u32_e32 vcc, s10, v40
	v_max3_f32 v49, v49, v72, v66
	v_max3_f32 v48, v48, v69, v50
	v_max3_f32 v49, v49, v73, v54
	v_max3_f32 v48, v48, v70, v52
	s_nop 0
	v_cndmask_b32_e32 v40, v210, v64, vcc
	v_max3_f32 v49, v49, v74, v55
	v_max3_f32 v48, v48, v71, v53
	v_max3_f32 v49, v49, v57, v41
	v_max3_f32 v48, v48, v43, v35
	v_max3_f32 v49, v49, v56, v38
	v_max3_f32 v48, v48, v42, v34
	v_max3_f32 v49, v49, v46, v39
	v_max3_f32 v48, v48, v44, v36
	v_max3_f32 v49, v49, v47, v40
	v_max3_f32 v48, v48, v45, v37
	v_max_f32_e32 v48, v48, v48
	v_max_f32_e32 v49, v49, v49
	v_max_f32_e32 v48, v49, v48
	v_mov_b32_e32 v49, v48
	s_nop 1
	v_permlane32_swap_b32_e32 v49, v48
	v_max_f32_e32 v48, v48, v49
	v_cmp_lt_f32_e64 s[28:29], s2, v48
	s_mov_b32 s2, 0x41000000
	v_cmp_lt_f32_e32 vcc, s2, v48
	s_mov_b32 s2, 0xc1000000
	v_cmp_gt_f32_e64 s[2:3], s2, v48
	s_and_b64 s[2:3], s[2:3], s[28:29]
	s_andn2_b64 s[2:3], s[2:3], s[24:25]
	s_or_b64 s[2:3], s[2:3], vcc
	s_and_b64 vcc, exec, s[2:3]
	s_cbranch_vccnz .LBB0_596

; template <int MODE>
; DI void bias_init(f32x16& s0, f32x16& s1, const TP& tp, float fbm, int hi) {
; #pragma unroll
;     for (int r = 0; r < 16; ++r) {
;         const int kvc = 16 * (r >> 3) + (r & 7);
;         if (MODE == 0) { s0[r] = __builtin_fmaf(-L2E, tp.cs[kvc + 8 * hi], fbm); s1[r] = __builtin_fmaf(-L2E, tp.cs[kvc + 32 + 8 * hi], fbm); }
;         else { s0[r] = __builtin_fmaf(tp.sl, (float)kvc, fbm); s1[r] = __builtin_fmaf(tp.sl, (float)(kvc + 32), fbm); }
;     }
; }
; DI float max3_asm(float a, float b, float c) { float r; asm("v_max3_f32 %0, %1, %2, %3" : "=v"(r) : "v"(a), "v"(b), "v"(c)); return r; }
; template <bool MASK>
; DI float mask_rowmax(f32x16& s0, f32x16& s1, const TP& tp) {
;     if (MASK) {
; #pragma unroll
;         for (int r = 0; r < 16; ++r) {
;             const int kvc = 16 * (r >> 3) + (r & 7);
;             const bool v0 = tp.sel && (kvc <= tp.lim) && (kvc > tp.lim2), v1 = tp.sel && (kvc + 32 <= tp.lim) && (kvc + 32 > tp.lim2);
;             s0[r] = v0 ? s0[r] : -1e30f; s1[r] = v1 ? s1[r] : -1e30f;
;         }
;     }
;     const float seed = __builtin_fminf(s0[15], s1[15]);
;     float ma = seed, mb = seed;
; #pragma unroll
;     for (int r = 0; r < 16; r += 2) { ma = max3_asm(ma, s0[r], s1[r]); mb = max3_asm(mb, s0[r + 1], s1[r + 1]); }
;     const float mx = fmaxf(ma, mb);
;     return fmaxf(mx, __shfl_xor(mx, 32));
; }
; template <int MODE, bool MASK, bool WITH_O>
; DI void attn_tile_t(lptr Kt, lptr Vt, const bf16x8 (&qf)[4], f32x16& o0, f32x16& o1, RowState& rs, const TP& tp, int lane) {
;     const int hi = lane >> 5;
;     f32x16 s0, s1;
;     bias_init<MODE>(s0, s1, tp, tp.fb - rs.mref, hi);
;     qk_acc(Kt, qf, s0, s1, lane);
;     const float mx = mask_rowmax<MASK>(s0, s1, tp);
;     const bool was = rs.seen; rs.seen = was || (mx > -1e29f);
;     const bool trig = (mx > 8.f) || (!was && mx > -1e29f && mx < -8.f);
;     if (__builtin_expect(__any(trig), 0)) {
; DI void slc_unit(const Params& P, lptr L, int u, int tid, int lane, int wid) {
;     ...
;         const int j = (int)list[jt], kv0 = j * 64;
;         const bool sel = (sm[ql * 8 + (j >> 5)] >> (j & 31)) & 1u;
;         if (__any(sel)) {
;             TP tp; tp.cs = nullptr; tp.sl = sl; tp.fb = sl * (float)(kv0 + 8 * hi - t); tp.lim = t - kv0 - 8 * hi; tp.lim2 = -(1 << 30); tp.sel = sel;
;             attn_tile<1>(Kt, Vt, qf, o0, o1, rs, tp, true, lane);
.LBB0_613:
	v_mov_b32_e32 v0, v253
	s_and_b32 s31, s0, 1
	v_and_b32_e32 v35, 31, v253
	s_waitcnt lgkmcnt(0)
	v_lshrrev_b32_e32 v36, v0, v255
	v_bfe_u32 v34, v255, v35, 1
	v_and_b32_e32 v35, 1, v36
	v_mov_b32_e32 v253, v254
	v_cmp_ne_u32_e32 vcc, 0, v34
	v_cmp_eq_u32_e64 s[28:29], 1, v35
	s_cbranch_vccz .LBB0_618
	s_mul_i32 s33, s31, 0x2400
	v_add_u32_e32 v232, s33, v170
	ds_read_b128 v[102:105], v232 offset:4608
	ds_read_b128 v[106:109], v232
	ds_read_b128 v[110:113], v232 offset:32
	ds_read_b128 v[114:117], v232 offset:4640
	ds_read_b128 v[118:121], v232 offset:64
	ds_read_b128 v[158:161], v232 offset:4672
	ds_read_b128 v[162:165], v232 offset:96
	ds_read_b128 v[166:169], v232 offset:4704
	v_lshl_or_b32 v0, v0, 6, v126
	v_sub_u32_e32 v34, v0, v91
	v_cvt_f32_i32_e32 v34, v34
	s_mov_b32 s0, 2.0
	v_sub_u32_e32 v152, v91, v0
	s_mov_b32 s1, 0x40400000
	v_cmp_lt_i32_e32 vcc, 54, v152
	v_fma_f32 v0, v150, v34, -v101
	s_cmp_eq_u64 vcc, exec
	s_cselect_b64 s[98:99], -1, 0
	s_orn2_b64 s[100:101], s[28:29], s[98:99]
	v_cndmask_b32_e64 v0, v210, v0, s[100:101]
	v_pk_fma_f32 v[36:37], v[94:95], s[0:1], v[0:1] op_sel_hi:[1,1,0]
	s_mov_b32 s0, 4.0
	s_mov_b32 s1, 0x40a00000
	v_pk_fma_f32 v[38:39], v[94:95], s[0:1], v[0:1] op_sel_hi:[1,1,0]
	s_mov_b32 s0, 0x40c00000
	s_mov_b32 s1, 0x40e00000
	v_pk_fma_f32 v[40:41], v[94:95], s[0:1], v[0:1] op_sel_hi:[1,1,0]
	s_mov_b32 s0, 0x41800000
	s_mov_b32 s1, 0x41880000
	v_pk_fma_f32 v[42:43], v[94:95], s[0:1], v[0:1] op_sel_hi:[1,1,0]
	s_mov_b32 s0, 0x41900000
	s_mov_b32 s1, 0x41980000
	v_pk_fma_f32 v[44:45], v[94:95], s[0:1], v[0:1] op_sel_hi:[1,1,0]
	s_mov_b32 s0, 0x41a00000
	s_mov_b32 s1, 0x41a80000
	v_mov_b32_e32 v151, v150
	v_fma_f32 v34, 0, v150, v0
	v_add_f32_e32 v35, v150, v0
	v_pk_fma_f32 v[46:47], v[94:95], s[0:1], v[0:1] op_sel_hi:[1,1,0]
	v_pk_fma_f32 v[48:49], v[94:95], s[18:19], v[0:1] op_sel_hi:[1,1,0]
	v_pk_fma_f32 v[64:65], v[150:151], s[4:5], v[0:1] op_sel_hi:[1,1,0]
	v_pk_fma_f32 v[62:63], v[150:151], s[14:15], v[0:1] op_sel_hi:[1,1,0]
	v_pk_fma_f32 v[60:61], v[150:151], s[16:17], v[0:1] op_sel_hi:[1,1,0]
	v_pk_fma_f32 v[58:59], v[150:151], s[94:95], v[0:1] op_sel_hi:[1,1,0]
	v_pk_fma_f32 v[56:57], v[150:151], s[96:97], v[0:1] op_sel_hi:[1,1,0]
	v_pk_fma_f32 v[54:55], v[150:151], s[84:85], v[0:1] op_sel_hi:[1,1,0]
	v_pk_fma_f32 v[52:53], v[150:151], s[72:73], v[0:1] op_sel_hi:[1,1,0]
	v_pk_fma_f32 v[50:51], v[96:97], s[44:45], v[0:1] op_sel_hi:[1,1,0]
	s_setprio 1
	s_waitcnt lgkmcnt(6)
	v_mfma_f32_32x32x16_bf16 v[34:49], v[106:109], v[66:69], v[34:49]
	v_mfma_f32_32x32x16_bf16 v[50:65], v[102:105], v[66:69], v[50:65]
	s_waitcnt lgkmcnt(5)
	v_mfma_f32_32x32x16_bf16 v[34:49], v[110:113], v[70:73], v[34:49]
	s_waitcnt lgkmcnt(4)
	v_mfma_f32_32x32x16_bf16 v[50:65], v[114:117], v[70:73], v[50:65]
	s_waitcnt lgkmcnt(3)
	v_mfma_f32_32x32x16_bf16 v[34:49], v[118:121], v[74:77], v[34:49]
	s_waitcnt lgkmcnt(2)
	v_mfma_f32_32x32x16_bf16 v[50:65], v[158:161], v[74:77], v[50:65]
	s_waitcnt lgkmcnt(1)
	v_mfma_f32_32x32x16_bf16 v[34:49], v[162:165], v[78:81], v[34:49]
	s_waitcnt lgkmcnt(0)
	v_mfma_f32_32x32x16_bf16 v[50:65], v[166:169], v[78:81], v[50:65]
	s_setprio 0
	s_and_b64 vcc, exec, s[98:99]
	s_cbranch_vccz .Lslc_masked
	s_nop 10
	v_max_f32_e32 v252, v65, v65
	v_max_f32_e32 v228, v49, v49
	v_min_f32_e32 v252, v228, v252
	v_max3_f32 v228, v252, v34, v50
	v_max3_f32 v252, v252, v35, v51
	s_mov_b32 s0, 0xefa18f08
	v_max3_f32 v228, v228, v36, v52
	v_max3_f32 v252, v252, v37, v53
	v_max3_f32 v228, v228, v38, v54
	v_max3_f32 v252, v252, v39, v55
	v_max3_f32 v228, v228, v40, v56
	v_max3_f32 v252, v252, v41, v57
	v_max3_f32 v228, v228, v42, v58
	v_max3_f32 v252, v252, v43, v59
	v_max3_f32 v228, v228, v44, v60
	v_max3_f32 v252, v252, v45, v61
	v_max3_f32 v228, v228, v46, v62
	v_max3_f32 v252, v252, v47, v63
	v_max3_f32 v228, v228, v48, v64
	v_max3_f32 v252, v252, v49, v65
	v_max_f32_e32 v252, v252, v252
	v_max_f32_e32 v228, v228, v228
	v_max_f32_e32 v252, v228, v252
	v_mov_b32_e32 v228, v252
	s_nop 1
	v_permlane32_swap_b32_e32 v228, v252
	v_max_f32_e32 v252, v252, v228
	v_cmp_lt_f32_e64 s[28:29], s0, v252
	s_mov_b32 s0, 0x41000000
	v_cmp_lt_f32_e32 vcc, s0, v252
	s_mov_b32 s0, 0xc1000000
	v_cmp_gt_f32_e64 s[0:1], s0, v252
	s_and_b64 s[0:1], s[0:1], s[28:29]
	s_andn2_b64 s[0:1], s[0:1], s[22:23]
	s_or_b64 s[0:1], s[0:1], vcc
	s_and_b64 vcc, exec, s[0:1]
	s_cbranch_vccnz .Lsf_rare
; template <int MODE, bool MASK, bool WITH_O>
; DI void attn_tile_t(lptr Kt, lptr Vt, const bf16x8 (&qf)[4], f32x16& o0, f32x16& o1, RowState& rs, const TP& tp, int lane) {
;     ...
;     } else {
;         const int i = lane & 31;
;         lptr vp = Vt + i * KPB + hi * 16;
;         float sum = 0.f;
;     ...
;         PV_STEP(s0, 0, 0) PV_STEP(s0, 8, 32) PV_STEP(s1, 0, 64) PV_STEP(s1, 8, 96)
;     ...
;         rs.l += sum;
	v_exp_f32_e32 v252, v34
	v_exp_f32_e32 v103, v35
	v_exp_f32_e32 v111, v36
	v_exp_f32_e32 v105, v37
	v_add_f32_e32 v106, 0, v252
	v_add_f32_e32 v106, v103, v106
	v_add_f32_e32 v104, v111, v106
	v_exp_f32_e32 v106, v38
	v_exp_f32_e32 v107, v39
	v_add_u32_e32 v228, s33, v172
	v_exp_f32_e32 v108, v40
	ds_read_b128 v[236:239], v228 offset:18432
	ds_read_b128 v[240:243], v228 offset:23040
	v_add_f32_e32 v104, v105, v104
	v_exp_f32_e32 v109, v41
	v_add_f32_e32 v104, v106, v104
	v_add_f32_e32 v104, v107, v104
	v_add_f32_e32 v104, v108, v104
	v_add_f32_e32 v110, v109, v104
	v_cvt_pk_bf16_f32 v104, v252, v103
	v_cvt_pk_bf16_f32 v105, v111, v105
	v_cvt_pk_bf16_f32 v106, v106, v107
	v_cvt_pk_bf16_f32 v107, v108, v109
	s_or_b64 s[22:23], s[22:23], s[28:29]
	s_waitcnt lgkmcnt(1)
	v_mfma_f32_32x32x16_bf16 v[18:33], v[236:239], v[104:107], v[18:33]
	s_waitcnt lgkmcnt(0)
	v_mfma_f32_32x32x16_bf16 v[2:17], v[240:243], v[104:107], v[2:17]
	v_exp_f32_e32 v252, v42
	v_exp_f32_e32 v43, v43
	v_exp_f32_e32 v103, v44
	v_exp_f32_e32 v44, v45
	v_add_f32_e32 v229, v252, v110
	v_exp_f32_e32 v45, v46
	v_add_f32_e32 v229, v43, v229
	v_exp_f32_e32 v46, v47
	v_add_f32_e32 v42, v103, v229
	v_exp_f32_e32 v47, v48
	ds_read_b128 v[236:239], v228 offset:18464
	ds_read_b128 v[240:243], v228 offset:23072
	v_add_f32_e32 v42, v44, v42
	v_exp_f32_e32 v48, v49
	v_add_f32_e32 v42, v45, v42
	v_add_f32_e32 v42, v46, v42
	v_add_f32_e32 v42, v47, v42
	v_add_f32_e32 v229, v48, v42
	v_cvt_pk_bf16_f32 v42, v252, v43
	v_cvt_pk_bf16_f32 v43, v103, v44
	v_cvt_pk_bf16_f32 v44, v45, v46
	v_cvt_pk_bf16_f32 v45, v47, v48
	s_waitcnt lgkmcnt(1)
	s_nop 0
	v_mfma_f32_32x32x16_bf16 v[18:33], v[236:239], v[42:45], v[18:33]
	s_waitcnt lgkmcnt(0)
	v_mfma_f32_32x32x16_bf16 v[2:17], v[240:243], v[42:45], v[2:17]
	v_exp_f32_e32 v230, v50
	v_exp_f32_e32 v51, v51
	v_exp_f32_e32 v231, v52
	v_exp_f32_e32 v52, v53
	v_add_f32_e32 v229, v230, v229
	v_exp_f32_e32 v53, v54
	v_add_f32_e32 v229, v51, v229
	v_exp_f32_e32 v54, v55
	v_add_f32_e32 v50, v231, v229
	v_exp_f32_e32 v55, v56
	ds_read_b128 v[42:45], v228 offset:18496
	ds_read_b128 v[46:49], v228 offset:23104
	v_add_f32_e32 v50, v52, v50
	v_exp_f32_e32 v41, v57
	v_add_f32_e32 v50, v53, v50
	v_add_f32_e32 v50, v54, v50
	v_add_f32_e32 v50, v55, v50
	v_add_f32_e32 v56, v41, v50
	v_cvt_pk_bf16_f32 v50, v230, v51
	v_cvt_pk_bf16_f32 v51, v231, v52
	v_cvt_pk_bf16_f32 v52, v53, v54
	v_cvt_pk_bf16_f32 v53, v55, v41
	s_waitcnt lgkmcnt(1)
	s_nop 0
	v_mfma_f32_32x32x16_bf16 v[18:33], v[42:45], v[50:53], v[18:33]
	s_waitcnt lgkmcnt(0)
	v_mfma_f32_32x32x16_bf16 v[2:17], v[46:49], v[50:53], v[2:17]
	v_exp_f32_e32 v38, v58
	v_exp_f32_e32 v34, v59
	v_exp_f32_e32 v0, v60
	v_exp_f32_e32 v35, v61
	v_add_f32_e32 v41, v38, v56
	v_exp_f32_e32 v36, v62
	ds_read_b128 v[42:45], v228 offset:18528
	ds_read_b128 v[46:49], v228 offset:23136
	v_add_f32_e32 v41, v34, v41
	v_exp_f32_e32 v37, v63
	v_exp_f32_e32 v39, v64
	v_exp_f32_e32 v40, v65
	v_add_f32_e32 v41, v0, v41
	v_add_f32_e32 v41, v35, v41
	v_add_f32_e32 v41, v36, v41
	v_add_f32_e32 v41, v37, v41
	v_cvt_pk_bf16_f32 v34, v38, v34
	v_cvt_pk_bf16_f32 v35, v0, v35
	v_cvt_pk_bf16_f32 v36, v36, v37
	v_cvt_pk_bf16_f32 v37, v39, v40
	v_add_f32_e32 v41, v39, v41
	v_add_f32_e32 v41, v40, v41
	s_waitcnt lgkmcnt(1)
	v_mfma_f32_32x32x16_bf16 v[18:33], v[42:45], v[34:37], v[18:33]
	s_waitcnt lgkmcnt(0)
	v_mfma_f32_32x32x16_bf16 v[2:17], v[46:49], v[34:37], v[2:17]
	v_add_f32_e32 v100, v100, v41
	s_branch .LBB0_618

; DI float max3_asm(float a, float b, float c) { float r; asm("v_max3_f32 %0, %1, %2, %3" : "=v"(r) : "v"(a), "v"(b), "v"(c)); return r; }
; template <bool MASK>
; DI float mask_rowmax(f32x16& s0, f32x16& s1, const TP& tp) {
;     ...
;     const float seed = __builtin_fminf(s0[15], s1[15]);
;     float ma = seed, mb = seed;
; #pragma unroll
;     for (int r = 0; r < 16; r += 2) { ma = max3_asm(ma, s0[r], s1[r]); mb = max3_asm(mb, s0[r + 1], s1[r + 1]); }
;     const float mx = fmaxf(ma, mb);
;     return fmaxf(mx, __shfl_xor(mx, 32));
; }
; template <int MODE, bool MASK, bool WITH_O>
; DI void attn_tile_t(lptr Kt, lptr Vt, const bf16x8 (&qf)[4], f32x16& o0, f32x16& o1, RowState& rs, const TP& tp, int lane) {
;     const int hi = lane >> 5;
;     f32x16 s0, s1;
;     bias_init<MODE>(s0, s1, tp, tp.fb - rs.mref, hi);
;     qk_acc(Kt, qf, s0, s1, lane);
;     const float mx = mask_rowmax<MASK>(s0, s1, tp);
;     const bool was = rs.seen; rs.seen = was || (mx > -1e29f);
;     const bool trig = (mx > 8.f) || (!was && mx > -1e29f && mx < -8.f);
;     if (__builtin_expect(__any(trig), 0)) {
.Lslc_join:
	v_max_f32_e32 v49, v40, v40
	v_max_f32_e32 v57, v48, v48
	v_min_f32_e32 v49, v57, v49
	v_max3_f32 v57, v49, v106, v102
	v_max3_f32 v49, v49, v103, v51
	s_mov_b32 s0, 0xefa18f08
	v_max3_f32 v57, v57, v104, v50
	v_max3_f32 v49, v49, v105, v52
	v_max3_f32 v57, v57, v107, v53
	v_max3_f32 v49, v49, v108, v54
	v_max3_f32 v57, v57, v109, v55
	v_max3_f32 v49, v49, v110, v41
	v_max3_f32 v57, v57, v56, v38
	v_max3_f32 v49, v49, v43, v34
	v_max3_f32 v57, v57, v42, v0
	v_max3_f32 v49, v49, v44, v35
	v_max3_f32 v57, v57, v45, v36
	v_max3_f32 v49, v49, v46, v37
	v_max3_f32 v57, v57, v47, v39
	v_max3_f32 v49, v49, v48, v40
	v_max_f32_e32 v49, v49, v49
	v_max_f32_e32 v57, v57, v57
	v_max_f32_e32 v49, v57, v49
	v_mov_b32_e32 v57, v49
	s_nop 1
	v_permlane32_swap_b32_e32 v57, v49
	v_max_f32_e32 v49, v49, v57
	v_cmp_lt_f32_e64 s[28:29], s0, v49
	s_mov_b32 s0, 0x41000000
	v_cmp_lt_f32_e32 vcc, s0, v49
	s_mov_b32 s0, 0xc1000000
	v_cmp_gt_f32_e64 s[0:1], s0, v49
	s_and_b64 s[0:1], s[0:1], s[28:29]
	s_andn2_b64 s[0:1], s[0:1], s[22:23]
	s_or_b64 s[0:1], s[0:1], vcc
	s_and_b64 vcc, exec, s[0:1]
	s_cbranch_vccnz .LBB0_622
